# v12 + P4c: chunk-state fragments shared through LDS by the 4 waves of an item (8 fragment loads per wave -> 2, one barrier per item)
# speedup vs baseline: 1.0085x; 1.0085x over previous
; __device__ __forceinline__ void chunk_out(const PBArgs& A, unsigned char* lds, int G_, int wave, int lane) {
;     const bf16* Y0g = (const bf16*)(A.dout + DO_Y0); const bf16* RPg = (const bf16*)(A.dout + DO_RP); const bf16* MC = (const bf16*)(A.ws + WS_MC);
;     const bf16* Vr = (const bf16*)(A.ws + WS_V); const bf16* Gt = (const bf16*)(A.ws + WS_HBUF); const float* RK = (const float*)(A.ws + WS_RK);
;     bf16* YA = (bf16*)(A.ws + WS_YA);
;     const int fr = lane & 15, fq = lane >> 4, tt = wave & 3, half = wave >> 2;
;     unsigned char* ostg = lds + wave * 2304;
;     bf16x8 nbR[2], naM[4][2]; u32x2 ny0[4]; u32x4 nrv[2], nrg[2]; f32x4 nr4;
;     ...
;     const int it0 = blockIdx.x * 2 + half;
;     if (it0 < 4096) CO_LOAD(it0);
.LBB0_575:
	s_or_b64 exec, exec, s[0:1]
	s_lshl_b32 s0, s68, 1
	v_readlane_b32 s1, v241, 27
	s_add_i32 s0, s1, s0
	s_cmpk_lt_i32 s0, 0x1000
	s_movk_i32 s2, 0x1000
	s_waitcnt lgkmcnt(0)
	s_barrier
	s_waitcnt vmcnt(3)
	v_mbcnt_lo_u32_b32 v60, -1, 0
	v_mbcnt_hi_u32_b32 v60, -1, v60
	s_cbranch_scc0 .LBB0_578
	s_add_u32 s3, s28, 0x19800000
	s_addc_u32 s16, s29, 0
	s_add_u32 s14, s26, 0x4000000
	s_addc_u32 s15, s27, 0
	v_readlane_b32 s1, v242, 17
	s_add_u32 s8, s26, 0x6000000
	s_mulk_i32 s1, 0x900
	s_addc_u32 s9, s27, 0
	s_add_i32 s17, s1, 0
	v_readlane_b32 s1, v242, 0
	s_bfe_u32 s18, s1, 0x20006
	s_ashr_i32 s1, s0, 31
	v_lshlrev_b32_e32 v94, 3, v60
	s_lshl_b64 s[6:7], s[0:1], 13
	v_lshl_add_u32 v0, s18, 10, v94
	s_add_u32 s10, s8, s6
	v_ashrrev_i32_e32 v1, 31, v0
	s_addc_u32 s11, s9, s7
	v_lshlrev_b64 v[62:63], 1, v[0:1]
	v_lshl_add_u64 v[4:5], s[10:11], 0, v[62:63]
	s_add_u32 s10, s3, s6
	s_addc_u32 s11, s16, s7
	v_lshlrev_b32_e32 v8, 2, v60
	s_add_u32 s6, s14, s6
	v_ashrrev_i32_e32 v9, 31, v8
	s_addc_u32 s7, s15, s7
	v_lshlrev_b64 v[64:65], 1, v[8:9]
	s_mov_b32 s5, 0
	v_lshl_add_u64 v[8:9], s[6:7], 0, v[64:65]
	s_lshl_b32 s4, s18, 9
	v_ashrrev_i32_e32 v95, 31, v94
	v_lshl_add_u64 v[20:21], v[8:9], 0, s[4:5]
	v_add_u32_e32 v96, 0x800, v94
	v_add_u32_e32 v98, 0xa00, v94
	v_add_u32_e32 v100, 0xc00, v94
	v_add_u32_e32 v102, 0xe00, v94
	v_lshl_add_u64 v[10:11], v[94:95], 1, s[10:11]
	v_ashrrev_i32_e32 v97, 31, v96
	v_ashrrev_i32_e32 v99, 31, v98
	v_add_co_u32_e32 v40, vcc, s2, v20
	v_ashrrev_i32_e32 v101, 31, v100
	v_ashrrev_i32_e32 v103, 31, v102
	global_load_dwordx4 v[0:3], v[4:5], off
	s_nop 0
	global_load_dwordx4 v[4:7], v[4:5], off offset:1024
	s_nop 0
	global_load_dwordx4 v[32:35], v[10:11], off
	global_load_dwordx4 v[36:39], v[10:11], off offset:1024
	global_load_dwordx4 v[16:19], v[10:11], off offset:2048
	global_load_dwordx4 v[24:27], v[10:11], off offset:3072
	global_load_dwordx2 v[112:113], v[20:21], off
	global_load_dwordx2 v[108:109], v[20:21], off offset:2048
	v_lshl_add_u64 v[8:9], v[96:97], 1, s[10:11]
	v_lshl_add_u64 v[12:13], v[98:99], 1, s[10:11]
	v_addc_co_u32_e32 v41, vcc, 0, v21, vcc
	v_lshl_add_u64 v[20:21], v[100:101], 1, s[10:11]
	v_lshl_add_u64 v[28:29], v[102:103], 1, s[10:11]
	s_ashr_i32 s10, s0, 6
	s_ashr_i32 s11, s10, 31
	s_lshl_b32 s1, s0, 6
	s_lshl_b64 s[12:13], s[10:11], 12
	s_and_b32 s1, s1, 0xfc0
	s_or_b32 s7, s12, s1
	s_lshl_b32 s6, s18, 4
	s_or_b32 s12, s7, s6
	s_lshl_b64 s[12:13], s[12:13], 7
	global_load_dwordx4 v[8:11], v[8:9], off
	s_nop 0
	global_load_dwordx4 v[12:15], v[12:13], off
	s_nop 0
	global_load_dwordx4 v[20:23], v[20:21], off
	s_nop 0
	global_load_dwordx4 v[28:31], v[28:29], off
	s_nop 0
	global_load_dwordx2 v[114:115], v[40:41], off
	global_load_dwordx2 v[110:111], v[40:41], off offset:2048
	s_add_u32 s18, s70, s12
	v_lshlrev_b32_e32 v40, 4, v60
	s_addc_u32 s19, s71, s13
	v_and_b32_e32 v66, 0x70, v40
	v_mov_b32_e32 v67, 0
	v_lshl_add_u64 v[48:49], s[18:19], 0, v[66:67]
	v_readlane_b32 s18, v241, 19
	v_readlane_b32 s19, v241, 20
	s_add_u32 s12, s18, s12
	s_addc_u32 s13, s19, s13
	v_lshl_add_u64 v[50:51], s[12:13], 0, v[66:67]
	s_ashr_i32 s12, s0, 9
	s_ashr_i32 s13, s12, 31
	v_and_b32_e32 v92, 15, v60
	s_lshl_b64 s[12:13], s[12:13], 12
	s_waitcnt vmcnt(16)
	v_or_b32_e32 v56, s12, v92
	v_ashrrev_i32_e32 v104, 3, v60
	v_or_b32_e32 v56, s1, v56
	v_add_u32_e32 v106, 8, v104
	v_or_b32_e32 v56, s6, v56
	v_mov_b32_e32 v57, s13
	v_readlane_b32 s22, v241, 48
	v_ashrrev_i32_e32 v105, 31, v104
	v_ashrrev_i32_e32 v107, 31, v106
	v_lshlrev_b64 v[56:57], 7, v[56:57]
	v_readlane_b32 s23, v241, 49
	s_lshl_b32 s1, s10, 4
	v_lshlrev_b64 v[40:41], 7, v[104:105]
	v_lshlrev_b64 v[52:53], 7, v[106:107]
	v_lshl_add_u64 v[56:57], s[22:23], 0, v[56:57]
	s_and_b32 s10, s1, 0x70
	s_mov_b32 s11, s5
	v_lshl_add_u64 v[42:43], v[48:49], 0, v[40:41]
	v_lshl_add_u64 v[40:41], v[50:51], 0, v[40:41]
	v_lshl_add_u64 v[48:49], v[48:49], 0, v[52:53]
	v_lshl_add_u64 v[50:51], v[50:51], 0, v[52:53]
	v_lshl_add_u64 v[56:57], v[56:57], 0, s[10:11]
	global_load_dwordx4 v[44:47], v[42:43], off
	s_nop 0
	global_load_dwordx4 v[40:43], v[40:41], off
	s_nop 0
	global_load_dwordx4 v[52:55], v[48:49], off
	s_nop 0
	global_load_dwordx4 v[48:51], v[50:51], off
	v_ashrrev_i32_e32 v70, 4, v60
	global_load_dwordx4 v[56:59], v[56:57], off
	s_movk_i32 s1, 0x90
	v_mov_b32_e32 v71, s17
	v_lshlrev_b32_e32 v74, 3, v70
	v_lshlrev_b32_e32 v70, 2, v70
	v_readlane_b32 s36, v242, 1
	v_mad_u32_u24 v73, v92, s1, v71
	v_lshl_add_u64 v[64:65], s[14:15], 0, v[64:65]
	v_ashrrev_i32_e32 v71, 31, v70
	v_readlane_b32 s38, v242, 3
	v_readlane_b32 s39, v242, 4
	v_readlane_b32 s40, v242, 5
	v_readlane_b32 s41, v242, 6
	v_lshlrev_b64 v[60:61], 6, v[104:105]
	v_lshlrev_b64 v[68:69], 6, v[106:107]
	v_add_u32_e32 v72, s17, v66
	v_lshl_add_u64 v[116:117], s[70:71], 0, v[66:67]
	v_lshl_add_u64 v[118:119], s[18:19], 0, v[66:67]
	v_lshl_add_u64 v[120:121], s[74:75], 0, v[66:67]
	v_mul_lo_u32 v66, v104, s1
	v_lshl_add_u64 v[122:123], v[64:65], 0, s[4:5]
	v_lshl_add_u64 v[124:125], s[8:9], 0, v[62:63]
	v_lshlrev_b64 v[62:63], 2, v[70:71]
	s_mov_b64 s[18:19], s[38:39]
	s_mov_b64 s[20:21], s[40:41]
	s_lshl_b32 s1, s68, 7
	v_readlane_b32 s4, v241, 23
	s_mov_b32 s7, s5
	s_lshl_b32 s10, s30, 1
	v_lshl_add_u64 v[126:127], s[18:19], 0, v[62:63]
	v_lshl_add_u64 v[128:129], s[20:21], 0, v[62:63]
	s_add_i32 s11, s1, s4
	s_lshl_b32 s12, s30, 7
	v_add_u32_e32 v93, v72, v66
	v_add_u32_e32 v144, v73, v74
	v_lshlrev_b64 v[130:131], 1, v[60:61]
	v_lshlrev_b64 v[132:133], 1, v[68:69]
	v_mov_b32_e32 v145, 0x3a27c5ac
	v_readlane_b32 s37, v242, 2
	v_readlane_b32 s42, v242, 7
	v_readlane_b32 s43, v242, 8
	v_readlane_b32 s44, v242, 9
	v_readlane_b32 s45, v242, 10
	v_readlane_b32 s46, v242, 11
	v_readlane_b32 s47, v242, 12
	v_readlane_b32 s48, v242, 13
	v_readlane_b32 s49, v242, 14
	v_readlane_b32 s50, v242, 15
	v_readlane_b32 s51, v242, 16
	v_mbcnt_lo_u32_b32 v154, -1, 0
	v_mbcnt_hi_u32_b32 v154, -1, v154
	v_readlane_b32 s98, v242, 17
	s_lshl_b32 s99, s98, 8
	v_lshl_add_u32 v155, v154, 2, s99
	v_readlane_b32 s100, v242, 3
	v_readlane_b32 s101, v242, 4
	s_nop 4
	global_load_dword v156, v155, s[100:101]
	v_readlane_b32 s100, v242, 5
	v_readlane_b32 s101, v242, 6
	s_nop 4
	global_load_dword v157, v155, s[100:101]
	v_add_u32_e32 v158, 32768, v155
	s_and_b32 s100, s98, 3
	s_lshl_b32 s101, s100, 9
	v_add_u32_e32 v170, s101, v94
	v_mov_b32_e32 v171, 0
	v_add_u32_e32 v172, 0x800, v170
	v_mov_b32_e32 v173, 0
	s_lshl_b32 s101, s100, 10
	s_lshr_b32 s100, s98, 2
	s_lshl_b32 s100, s100, 13
	v_lshlrev_b32_e32 v168, 4, v154
	v_add_u32_e32 v168, s100, v168
	v_add_u32_e32 v168, 40960, v168
	v_add_u32_e32 v166, s101, v168
	s_mov_b32 s99, 0
	s_mov_b32 s100, s0
	s_ashr_i32 s101, s0, 31
	s_lshl_b64 s[100:101], s[100:101], 13
	s_add_u32 s100, s100, s3
	s_addc_u32 s101, s101, s16
	v_lshl_add_u64 v[164:165], v[170:171], 1, s[100:101]
	v_lshl_add_u64 v[178:179], v[172:173], 1, s[100:101]
	global_load_dwordx4 v[160:163], v[164:165], off
	global_load_dwordx4 v[174:177], v[178:179], off
	s_waitcnt vmcnt(0)
; #define LDS_WAIT() asm volatile("s_waitcnt lgkmcnt(0)" ::: "memory")
; __device__ __forceinline__ f32x4 bf4(u32x2 w) { return (f32x4){__uint_as_float(w.x << 16), __uint_as_float(w.x & 0xffff0000u), __uint_as_float(w.y << 16), __uint_as_float(w.y & 0xffff0000u)}; }
; __device__ __forceinline__ void chunk_out(const PBArgs& A, unsigned char* lds, int G_, int wave, int lane) {
;     ...
;     for (int it = it0; it < 4096; it += 2 * G_) {
;         const int bh = it >> 6, ck = it & 63, b = bh >> 3, h = bh & 7;
;         bf16x8 bR[2], aM[4][2]; u32x2 y0[4], vv[4], gg[4]; u32x4 rv[2], rg[2];
; #pragma unroll
;         for (int ks = 0; ks < 2; ++ks) bR[ks] = nbR[ks];
; #pragma unroll
;         for (int vi = 0; vi < 4; ++vi) { aM[vi][0] = naM[vi][0]; aM[vi][1] = naM[vi][1]; y0[vi] = ny0[vi]; }
; #pragma unroll
;         for (int j = 0; j < 2; ++j) { rv[j] = nrv[j]; rg[j] = nrg[j]; }
;         const float rk = (nr4[0] + nr4[1]) + (nr4[2] + nr4[3]);
;         {
; #pragma unroll
;             for (int j = 0; j < 2; ++j) { const int tk = (lane >> 3) + 8 * j, c16 = lane & 7; *(u32x4*)(ostg + tk * 144 + c16 * 16) = rv[j]; }
;             LDS_WAIT();
; #pragma unroll
;             for (int vi = 0; vi < 4; ++vi) vv[vi] = *(const u32x2*)(ostg + fr * 144 + (vi * 16 + fq * 4) * 2);
;             LDS_WAIT();
; #pragma unroll
;             for (int j = 0; j < 2; ++j) { const int tk = (lane >> 3) + 8 * j, c16 = lane & 7; *(u32x4*)(ostg + tk * 144 + c16 * 16) = rg[j]; }
;             LDS_WAIT();
; #pragma unroll
;             for (int vi = 0; vi < 4; ++vi) gg[vi] = *(const u32x2*)(ostg + fr * 144 + (vi * 16 + fq * 4) * 2);
;             LDS_WAIT();
;         }
;         f32x4 c[4];
; #pragma unroll
;         for (int vi = 0; vi < 4; ++vi) {
;             c[vi] = bf4(y0[vi]);
; #pragma unroll
;             for (int ks = 0; ks < 2; ++ks) c[vi] = __builtin_amdgcn_mfma_f32_16x16x32_bf16(aM[vi][ks], bR[ks], c[vi], 0, 0, 0);
;         }
;         { const int itn = (it + 2 * G_ < 4096) ? it + 2 * G_ : it; CO_LOAD(itn); }
	ds_write_b32 v158, v156
	ds_write_b32 v158, v157 offset:2048
	v_lshrrev_b32_e32 v159, 4, v154
	v_lshlrev_b32_e32 v159, 4, v159
	v_add_u32_e32 v159, 32768, v159
	s_waitcnt lgkmcnt(0)
	s_barrier
.LBB0_577:
	s_waitcnt vmcnt(4)
	v_add_u32_e32 v167, s99, v166
	ds_write_b128 v167, v[160:163]
	ds_write_b128 v167, v[174:177] offset:4096
	ds_write_b128 v93, v[44:47]
	s_waitcnt vmcnt(2)
	ds_write_b128 v93, v[52:55] offset:1152
	s_waitcnt lgkmcnt(0)
	s_barrier
	v_add_u32_e32 v169, s99, v168
	ds_read_b128 v[32:35], v169
	ds_read_b128 v[36:39], v169 offset:1024
	ds_read_b128 v[16:19], v169 offset:2048
	ds_read_b128 v[24:27], v169 offset:3072
	ds_read_b128 v[8:11], v169 offset:4096
	ds_read_b128 v[12:15], v169 offset:5120
	ds_read_b128 v[20:23], v169 offset:6144
	ds_read_b128 v[28:31], v169 offset:7168
	s_xor_b32 s99, s99, 0x4000
	ds_read2_b64 v[68:71], v144 offset1:4
	ds_read2_b64 v[60:63], v144 offset0:8 offset1:12
	s_waitcnt lgkmcnt(0)
	ds_write_b128 v93, v[40:43]
	s_waitcnt vmcnt(1)
	ds_write_b128 v93, v[48:51] offset:1152
	v_lshlrev_b32_e32 v40, 16, v112
	v_and_b32_e32 v41, 0xffff0000, v112
	v_lshlrev_b32_e32 v42, 16, v113
	v_and_b32_e32 v43, 0xffff0000, v113
	s_ashr_i32 s8, s0, 9
	s_and_b32 s14, s0, 0x1c0
	v_mfma_f32_16x16x32_bf16 v[32:35], v[32:35], v[0:3], v[40:43]
	s_add_i32 s13, s0, s10
	s_cmpk_lt_i32 s13, 0x1000
	s_cselect_b64 s[18:19], -1, 0
	v_mfma_f32_16x16x32_bf16 v[88:91], v[36:39], v[4:7], v[32:35]
	s_and_b64 vcc, s[18:19], exec
	s_cselect_b32 s18, s13, s0
	s_ashr_i32 s19, s18, 31
	s_nop 0
	v_lshlrev_b32_e32 v32, 16, v108
	v_and_b32_e32 v33, 0xffff0000, v108
	v_lshlrev_b32_e32 v34, 16, v109
	v_and_b32_e32 v35, 0xffff0000, v109
	v_add_f32_e32 v136, v88, v89
	v_add_f32_e32 v137, v90, v91
	v_mfma_f32_16x16x32_bf16 v[16:19], v[16:19], v[0:3], v[32:35]
	v_add_f32_e32 v136, v136, v137
	v_add_f32_e32 v136, 0, v136
	s_lshl_b64 s[0:1], s[18:19], 13
	v_mfma_f32_16x16x32_bf16 v[76:79], v[24:27], v[4:7], v[16:19]
	s_add_u32 s20, s3, s0
	s_addc_u32 s21, s16, s1
	s_waitcnt lgkmcnt(0)
	ds_read2_b64 v[72:75], v144 offset1:4
	ds_read2_b64 v[64:67], v144 offset0:8 offset1:12
	v_lshlrev_b32_e32 v16, 16, v114
	v_and_b32_e32 v17, 0xffff0000, v114
	v_lshlrev_b32_e32 v18, 16, v115
	v_and_b32_e32 v19, 0xffff0000, v115
	v_add_f32_e32 v137, v76, v77
	v_add_f32_e32 v138, v78, v79
	v_mfma_f32_16x16x32_bf16 v[8:11], v[8:11], v[0:3], v[16:19]
	v_add_f32_e32 v137, v137, v138
	v_add_f32_e32 v136, v136, v137
	s_waitcnt lgkmcnt(0)
	v_mfma_f32_16x16x32_bf16 v[80:83], v[12:15], v[4:7], v[8:11]
	v_lshl_add_u64 v[12:13], v[98:99], 1, s[20:21]
	s_waitcnt vmcnt(0)
	v_mov_b32_e32 v44, v57
	v_mov_b32_e32 v45, v58
	s_nop 0
	v_lshlrev_b32_e32 v8, 16, v110
	v_and_b32_e32 v9, 0xffff0000, v110
	v_lshlrev_b32_e32 v10, 16, v111
	v_and_b32_e32 v11, 0xffff0000, v111
	v_add_f32_e32 v137, v80, v81
	v_add_f32_e32 v138, v82, v83
	v_mfma_f32_16x16x32_bf16 v[0:3], v[20:23], v[0:3], v[8:11]
	v_add_f32_e32 v137, v137, v138
	v_add_f32_e32 v136, v136, v137
	v_lshl_add_u64 v[20:21], v[122:123], 0, s[0:1]
	v_mfma_f32_16x16x32_bf16 v[84:87], v[28:31], v[4:7], v[0:3]
	v_lshl_add_u64 v[4:5], v[124:125], 0, s[0:1]
	v_add_co_u32_e64 v40, s[0:1], s2, v20
	v_lshl_add_u64 v[8:9], v[94:95], 1, s[20:21]
	v_lshl_add_u64 v[164:165], v[170:171], 1, s[20:21]
	v_lshl_add_u64 v[178:179], v[172:173], 1, s[20:21]
	s_nop 0
	v_addc_co_u32_e64 v41, s[0:1], 0, v21, s[0:1]
	s_nop 2
	v_add_f32_e32 v137, v84, v85
	v_add_f32_e32 v138, v86, v87
	v_add_f32_e32 v137, v137, v138
	v_add_f32_e32 v136, v136, v137
	v_mov_b32_e32 v137, v136
	s_nop 1
	v_permlane32_swap_b32_e32 v136, v137
	v_add_f32_e32 v136, v136, v137
	v_mov_b32_e32 v137, v136
	s_nop 1
	v_permlane16_swap_b32_e32 v136, v137
	v_add_f32_e32 v136, v136, v137
	v_fmamk_f32 v151, v136, 0xbc800000, v91
	v_fmac_f32_e32 v89, 0xbc800000, v136
	v_fmamk_f32 v150, v136, 0xbc800000, v90
	v_fmamk_f32 v88, v136, 0xbc800000, v88
	v_mul_f32_e32 v90, v89, v89
	v_mul_f32_e32 v91, v151, v151
	v_fmac_f32_e32 v90, v88, v88
	v_fmac_f32_e32 v91, v150, v150
	s_ashr_i32 s0, s18, 6
	v_add_f32_e32 v137, v90, v91
	v_fmamk_f32 v91, v136, 0xbc800000, v79
	v_fmac_f32_e32 v77, 0xbc800000, v136
	s_ashr_i32 s1, s0, 31
	v_fmamk_f32 v90, v136, 0xbc800000, v78
	v_fmamk_f32 v76, v136, 0xbc800000, v76
	v_mul_f32_e32 v78, v77, v77
	v_mul_f32_e32 v79, v91, v91
	global_load_dwordx4 v[0:3], v[4:5], off
	s_nop 0
	global_load_dwordx4 v[4:7], v[4:5], off offset:1024
	s_nop 0
	global_load_dwordx4 v[160:163], v[164:165], off
	global_load_dwordx4 v[174:177], v[178:179], off
	global_load_dwordx2 v[112:113], v[20:21], off
	s_nop 0
	s_nop 0
	global_load_dwordx2 v[108:109], v[20:21], off offset:2048
	v_lshl_add_u64 v[8:9], v[96:97], 1, s[20:21]
	v_lshl_add_u64 v[20:21], v[100:101], 1, s[20:21]
	v_lshl_add_u64 v[28:29], v[102:103], 1, s[20:21]
	s_lshl_b64 s[20:21], s[0:1], 12
	s_lshl_b32 s1, s18, 6
	s_ashr_i32 s18, s18, 9
	v_fmac_f32_e32 v78, v76, v76
	v_fmac_f32_e32 v79, v90, v90
	s_ashr_i32 s19, s18, 31
	v_add_f32_e32 v78, v78, v79
	v_fmamk_f32 v83, v136, 0xbc800000, v83
	v_fmac_f32_e32 v81, 0xbc800000, v136
	v_mov_b32_e32 v57, v59
	s_lshl_b64 s[18:19], s[18:19], 12
	v_add_f32_e32 v78, v137, v78
	v_fmamk_f32 v82, v136, 0xbc800000, v82
	v_fmamk_f32 v80, v136, 0xbc800000, v80
	v_mul_f32_e32 v79, v81, v81
	v_mul_f32_e32 v137, v83, v83
	v_pk_add_f32 v[134:135], v[44:45], v[56:57]
	s_and_b32 s1, s1, 0xfc0
	v_or_b32_e32 v56, s18, v92
	v_fmac_f32_e32 v79, v80, v80
	v_fmac_f32_e32 v137, v82, v82
	v_or_b32_e32 v56, s1, v56
	v_add_f32_e32 v79, v79, v137
	v_mov_b32_e32 v57, s19
	v_or_b32_e32 v56, s6, v56
	v_add_f32_e32 v137, v79, v78
	v_fmamk_f32 v79, v136, 0xbc800000, v87
	v_fmac_f32_e32 v85, 0xbc800000, v136
; __device__ __forceinline__ unsigned pk2(float lo, float hi) { f32x2_t v = {lo, hi}; bf16x2_t b = __builtin_convertvector(v, bf16x2_t); return __builtin_bit_cast(unsigned, b); }
; #define LDS_WAIT() asm volatile("s_waitcnt lgkmcnt(0)" ::: "memory")
; __device__ __forceinline__ f32x4 bf4(u32x2 w) { return (f32x4){__uint_as_float(w.x << 16), __uint_as_float(w.x & 0xffff0000u), __uint_as_float(w.y << 16), __uint_as_float(w.y & 0xffff0000u)}; }
; __device__ __forceinline__ void chunk_out(const PBArgs& A, unsigned char* lds, int G_, int wave, int lane) {
;     ...
;         { const int itn = (it + 2 * G_ < 4096) ? it + 2 * G_ : it; CO_LOAD(itn); }
;         float sm = 0.f;
; #pragma unroll
;         for (int vi = 0; vi < 4; ++vi) sm += (c[vi][0] + c[vi][1]) + (c[vi][2] + c[vi][3]);
;         sm = rows4_sum(sm);
;         const float mu = sm * (1.0f / 64.0f);
;         float q = 0.f;
; #pragma unroll
;         for (int vi = 0; vi < 4; ++vi) { c[vi] = c[vi] - mu; q += (c[vi][0] * c[vi][0] + c[vi][1] * c[vi][1]) + (c[vi][2] * c[vi][2] + c[vi][3] * c[vi][3]); }
;         q = rows4_sum(q);
;         const float rs = rsqrtf(q * (1.0f / 64.0f) + 64e-5f);
; #pragma unroll
;         for (int vi = 0; vi < 4; ++vi) {
;             const f32x4 lg = *(const f32x4*)(A.lnx_g + h * 64 + vi * 16 + fq * 4), lb = *(const f32x4*)(A.lnx_b + h * 64 + vi * 16 + fq * 4);
;             const f32x4 o = (c[vi] * rs * lg + lb + bf4(vv[vi]) * rk) * bf4(gg[vi]);
;             *(u32x2*)(ostg + fr * 144 + (vi * 16 + fq * 4) * 2) = (u32x2){pk2(o[0], o[1]), pk2(o[2], o[3])};
;         }
;         LDS_WAIT();
; #pragma unroll
;         for (int j = 0; j < 2; ++j) {
;             const int tk = (lane >> 3) + 8 * j, c16 = lane & 7;
;             const size_t tg = (size_t)b * SEQ + ck * 64 + tt * 16 + tk;
;             *(u32x4*)(YA + tg * 512 + h * 64 + c16 * 8) = *(const u32x4*)(ostg + tk * 144 + c16 * 16);
;         }
;         LDS_WAIT();
	v_lshlrev_b64 v[56:57], 7, v[56:57]
	s_lshl_b32 s0, s0, 4
	v_fmamk_f32 v78, v136, 0xbc800000, v86
	v_fmamk_f32 v84, v136, 0xbc800000, v84
	v_mul_f32_e32 v86, v85, v85
	v_mul_f32_e32 v87, v79, v79
	v_lshl_add_u64 v[56:57], s[22:23], 0, v[56:57]
	s_and_b32 s4, s0, 0x70
	v_fmac_f32_e32 v86, v84, v84
	v_fmac_f32_e32 v87, v78, v78
	v_lshl_add_u64 v[56:57], v[56:57], 0, s[4:5]
	v_add_f32_e32 v86, v86, v87
	s_lshl_b32 s4, s14, 2
	v_add_f32_e32 v86, v86, v137
	v_add_u32_e32 v136, s4, v159
	s_nop 0
	s_nop 0
	v_mov_b32_e32 v87, v86
	s_nop 0
	s_nop 0
	v_permlane32_swap_b32_e32 v86, v87
	global_load_dwordx2 v[114:115], v[40:41], off
	v_add_f32_e32 v86, v86, v87
	s_nop 0
	s_nop 0
	s_nop 0
	s_nop 0
	global_load_dwordx2 v[110:111], v[40:41], off offset:2048
	ds_read_b128 v[140:143], v136
	ds_read_b128 v[146:149], v136 offset:2048
	v_mov_b32_e32 v87, v86
	s_nop 1
	v_permlane16_swap_b32_e32 v86, v87
	v_add_f32_e32 v86, v86, v87
	v_fmamk_f32 v86, v86, 0x3c800000, v145
	s_mov_b32 s0, 0x800000
	s_or_b32 s20, s20, s1
	v_cmp_gt_f32_e64 s[0:1], s0, v86
	v_mul_f32_e32 v87, 0x4b800000, v86
	s_or_b64 s[20:21], s[20:21], s[6:7]
	v_cndmask_b32_e64 v86, v86, v87, s[0:1]
	v_rsq_f32_e32 v86, v86
	s_lshl_b64 s[20:21], s[20:21], 7
	v_lshl_add_u64 v[48:49], v[116:117], 0, s[20:21]
	v_lshl_add_u64 v[50:51], v[118:119], 0, s[20:21]
	v_mul_f32_e32 v87, 0x45800000, v86
	v_cndmask_b32_e64 v86, v86, v87, s[0:1]
	v_pk_mul_f32 v[152:153], v[88:89], v[86:87] op_sel_hi:[1,0]
	v_pk_mul_f32 v[88:89], v[150:151], v[86:87] op_sel_hi:[1,0]
	v_lshl_add_u64 v[40:41], v[48:49], 0, v[130:131]
	v_lshl_add_u64 v[48:49], v[48:49], 0, v[132:133]
	v_add_f32_e32 v134, v134, v135
	global_load_dwordx4 v[44:47], v[40:41], off
	global_load_dwordx4 v[52:55], v[48:49], off
	v_lshl_add_u64 v[40:41], v[50:51], 0, v[130:131]
	v_lshl_add_u64 v[48:49], v[50:51], 0, v[132:133]
	global_load_dwordx4 v[40:43], v[40:41], off
	s_ashr_i32 s9, s8, 31
	global_load_dwordx4 v[48:51], v[48:49], off
	s_and_b32 s4, s11, 0xfc0
	global_load_dwordx4 v[56:59], v[56:57], off
	s_lshl_b64 s[0:1], s[8:9], 12
	s_or_b32 s4, s4, s6
	s_or_b32 s0, s0, s4
	s_lshl_b32 s4, s14, 1
	s_add_i32 s11, s11, s12
	s_nop 0
	s_waitcnt lgkmcnt(0)
	v_pk_fma_f32 v[88:89], v[142:143], v[88:89], v[148:149]
	v_pk_fma_f32 v[140:141], v[140:141], v[152:153], v[146:147]
	s_nop 0
	v_lshlrev_b32_e32 v142, 16, v68
	v_and_b32_e32 v143, 0xffff0000, v68
	v_lshlrev_b32_e32 v68, 16, v69
	v_and_b32_e32 v69, 0xffff0000, v69
	v_pk_fma_f32 v[140:141], v[134:135], v[142:143], v[140:141] op_sel_hi:[0,1,1]
	v_pk_fma_f32 v[68:69], v[134:135], v[68:69], v[88:89] op_sel_hi:[0,1,1]
	s_nop 0
	v_lshlrev_b32_e32 v88, 16, v72
	v_and_b32_e32 v89, 0xffff0000, v72
	v_lshlrev_b32_e32 v72, 16, v73
	v_and_b32_e32 v73, 0xffff0000, v73
	v_pk_mul_f32 v[68:69], v[68:69], v[72:73]
	v_pk_mul_f32 v[72:73], v[140:141], v[88:89]
	ds_read_b128 v[140:143], v136 offset:64
	ds_read_b128 v[146:149], v136 offset:2112
	v_cvt_pk_bf16_f32 v72, v72, v73
	v_cvt_pk_bf16_f32 v73, v68, v69
	v_pk_mul_f32 v[68:69], v[76:77], v[86:87] op_sel_hi:[1,0]
	v_pk_mul_f32 v[76:77], v[90:91], v[86:87] op_sel_hi:[1,0]
	v_lshlrev_b32_e32 v88, 16, v70
	v_and_b32_e32 v89, 0xffff0000, v70
	v_lshlrev_b32_e32 v70, 16, v71
	v_and_b32_e32 v71, 0xffff0000, v71
	s_nop 0
	s_waitcnt lgkmcnt(0)
	v_pk_fma_f32 v[76:77], v[142:143], v[76:77], v[148:149]
	v_pk_fma_f32 v[68:69], v[140:141], v[68:69], v[146:147]
	v_pk_fma_f32 v[70:71], v[134:135], v[70:71], v[76:77] op_sel_hi:[0,1,1]
	v_pk_fma_f32 v[68:69], v[134:135], v[88:89], v[68:69] op_sel_hi:[0,1,1]
	v_lshlrev_b32_e32 v76, 16, v74
	v_and_b32_e32 v77, 0xffff0000, v74
	v_lshlrev_b32_e32 v74, 16, v75
	v_and_b32_e32 v75, 0xffff0000, v75
	v_pk_mul_f32 v[70:71], v[70:71], v[74:75]
	v_pk_mul_f32 v[68:69], v[68:69], v[76:77]
	v_pk_mul_f32 v[76:77], v[80:81], v[86:87] op_sel_hi:[1,0]
	v_cvt_pk_bf16_f32 v68, v68, v69
	v_cvt_pk_bf16_f32 v69, v70, v71
	ds_write2_b64 v144, v[72:73], v[68:69] offset1:4
	ds_read_b128 v[68:71], v136 offset:128
	ds_read_b128 v[72:75], v136 offset:2176
	v_pk_mul_f32 v[80:81], v[82:83], v[86:87] op_sel_hi:[1,0]
	s_nop 0
	s_waitcnt lgkmcnt(0)
	v_pk_fma_f32 v[68:69], v[68:69], v[76:77], v[72:73]
	v_pk_fma_f32 v[70:71], v[70:71], v[80:81], v[74:75]
	v_lshlrev_b32_e32 v72, 16, v60
	v_and_b32_e32 v73, 0xffff0000, v60
	v_lshlrev_b32_e32 v60, 16, v61
	v_and_b32_e32 v61, 0xffff0000, v61
	v_pk_fma_f32 v[68:69], v[134:135], v[72:73], v[68:69] op_sel_hi:[0,1,1]
	v_pk_fma_f32 v[60:61], v[134:135], v[60:61], v[70:71] op_sel_hi:[0,1,1]
	s_nop 0
	v_lshlrev_b32_e32 v70, 16, v64
	v_and_b32_e32 v71, 0xffff0000, v64
	v_lshlrev_b32_e32 v64, 16, v65
	v_and_b32_e32 v65, 0xffff0000, v65
	v_pk_mul_f32 v[60:61], v[60:61], v[64:65]
	v_pk_mul_f32 v[64:65], v[68:69], v[70:71]
	ds_read_b128 v[68:71], v136 offset:192
	ds_read_b128 v[72:75], v136 offset:2240
	v_cvt_pk_bf16_f32 v64, v64, v65
	v_cvt_pk_bf16_f32 v65, v60, v61
	v_pk_mul_f32 v[60:61], v[84:85], v[86:87] op_sel_hi:[1,0]
	v_pk_mul_f32 v[76:77], v[78:79], v[86:87] op_sel_hi:[1,0]
	s_nop 0
	s_waitcnt lgkmcnt(0)
	v_pk_fma_f32 v[60:61], v[68:69], v[60:61], v[72:73]
	v_pk_fma_f32 v[70:71], v[70:71], v[76:77], v[74:75]
	v_lshlrev_b32_e32 v68, 16, v62
	v_and_b32_e32 v69, 0xffff0000, v62
	v_lshlrev_b32_e32 v62, 16, v63
	v_and_b32_e32 v63, 0xffff0000, v63
	v_pk_fma_f32 v[60:61], v[134:135], v[68:69], v[60:61] op_sel_hi:[0,1,1]
	v_pk_fma_f32 v[62:63], v[134:135], v[62:63], v[70:71] op_sel_hi:[0,1,1]
	v_lshlrev_b32_e32 v68, 16, v66
	v_and_b32_e32 v69, 0xffff0000, v66
	v_lshlrev_b32_e32 v66, 16, v67
	v_and_b32_e32 v67, 0xffff0000, v67
	v_pk_mul_f32 v[62:63], v[62:63], v[66:67]
	v_pk_mul_f32 v[60:61], v[60:61], v[68:69]
	v_lshl_add_u64 v[66:67], s[0:1], 0, v[104:105]
	v_cvt_pk_bf16_f32 v60, v60, v61
	v_cvt_pk_bf16_f32 v61, v62, v63
	ds_write2_b64 v144, v[64:65], v[60:61] offset0:8 offset1:12
	s_waitcnt lgkmcnt(0)
	ds_read_b128 v[60:63], v93
	v_lshl_add_u64 v[64:65], v[120:121], 0, s[4:5]
	v_lshlrev_b64 v[66:67], 10, v[66:67]
	v_lshl_add_u64 v[66:67], v[64:65], 0, v[66:67]
	s_nop 0
	s_waitcnt lgkmcnt(0)
	global_store_dwordx4 v[66:67], v[60:63], off
	ds_read_b128 v[60:63], v93 offset:1152
	v_lshl_add_u64 v[66:67], s[0:1], 0, v[106:107]
	v_lshlrev_b64 v[66:67], 10, v[66:67]
	v_lshl_add_u64 v[64:65], v[64:65], 0, v[66:67]
	s_mov_b32 s0, s13
	s_nop 0
	s_waitcnt lgkmcnt(0)
	global_store_dwordx4 v[64:65], v[60:63], off
	s_waitcnt lgkmcnt(0)
	s_cbranch_vccnz .LBB0_577
